# sample-row split-K GEMM K=2816 (P2, P12): whole-line wave loads (8 rows x 128 B per instruction), 4 K-chunks in flight, MFMA fragments through a per-wave LDS staging area; K split over waves on line b
# speedup vs baseline: 1.0130x; 1.0074x over previous
; template <int MODE>
; __device__ __forceinline__ void small_gemm(LAS unsigned char* lds, const bf16* A, const bf16* Bt, int N, int K, bf16* O, int ldc, int act_cols, const float* bias, const bf16* Yv, int ldy, int it0, int it1) {
;     ...
;     for (int it = it0; it < it1; ++it) {
;         const int item = BX + it * GSZ; if (item >= nitems) break;
;         const int rt = item & 3, ct = item >> 2;
;         const int hc = 32 * ct + tl;
;         const int brow = (MODE == 3) ? (256 * (hc >> 7) + (hc & 127)) : hc;
;         const bf16* ap = A + (size_t)(32 * rt + tl) * K + wave * kw + 8 * hh;
;         const bf16* bp = Bt + (size_t)brow * K + wave * kw + 8 * hh;
;         v16f acc0, acc1;
; #pragma unroll
;         for (int r = 0; r < 16; ++r) { acc0[r] = 0.f; acc1[r] = 0.f; }
; #pragma unroll 4
;         for (int ks = 0; ks < nks; ++ks) {
;             const bfx8 a = *(const bfx8*)(ap + 16 * ks);
;             const bfx8 b0 = *(const bfx8*)(bp + 16 * ks);
;             acc0 = __builtin_amdgcn_mfma_f32_32x32x16_bf16(b0, a, acc0, 0, 0, 0);
;             if (MODE == 3) { const bfx8 b1 = *(const bfx8*)(bp + (size_t)128 * K + 16 * ks); acc1 = __builtin_amdgcn_mfma_f32_32x32x16_bf16(b1, a, acc1, 0, 0, 0); }
;         }
.LBB0_280:
	s_add_i32 s10, s10, s94
	s_cmpk_gt_i32 s10, 0x7f
	s_mov_b64 s[8:9], -1
	s_cbranch_scc1 .LBB0_279
	s_and_b32 s3, s13, 0xffffffe0
	v_or_b32_e32 v0, s3, v22
	v_mad_i64_i32 v[54:55], s[0:1], v0, s11, v[20:21]
	v_and_b32_e32 v246, 63, v182
	v_lshrrev_b32_e32 v247, 6, v182
	s_nop 0
	v_readfirstlane_b32 s98, v247
	s_and_b32 s8, s14, 0x60
	s_mov_b32 s100, s8
	v_or_b32_e32 v16, s8, v22
	v_mad_u64_u32 v[56:57], s[0:1], v16, s11, v[18:19]
	s_add_i32 s12, s12, -1
	s_add_i32 s13, s13, s46
	s_add_i32 s14, s14, s71
	v_lshlrev_b32_e32 v16, 11, v16
	s_cmp_eq_u32 s12, 0
	s_cselect_b64 s[8:9], -1, 0
	s_min_u32 s99, s98, 4
	s_lshl_b32 s99, s99, 7
	s_mul_i32 m0, s98, 0x280
	s_add_i32 s99, s99, m0
	s_mul_i32 m0, s98, 0x2c0
	s_sub_i32 s99, s99, m0
	v_lshrrev_b32_e32 v247, 3, v246
	v_and_b32_e32 v250, 7, v246
	v_lshlrev_b32_e32 v250, 4, v250
	s_mul_i32 m0, s98, 0x2400
	s_add_i32 m0, m0, 0x10000
	v_mul_u32_u24_e32 v248, 0x90, v247
	v_add3_u32 v248, v248, v250, m0
	v_mul_u32_u24_e32 v249, 0x90, v22
	v_lshrrev_b32_e32 v252, 5, v246
	v_lshl_add_u32 v249, v252, 4, v249
	v_add_u32_e32 v249, m0, v249
	v_lshlrev_b32_e32 v252, 4, v252
	v_sub_u32_e32 v252, v250, v252
	v_add_u32_e32 v252, s99, v252
	v_ashrrev_i32_e32 v253, 31, v252
	v_add_u32_e32 v246, s3, v247
	v_lshl_add_u64 v[194:195], v[20:21], 0, v[252:253]
	v_mad_u64_u32 v[192:193], vcc, v246, s11, v[194:195]
	v_add_u32_e32 v246, s100, v247
	v_lshl_add_u64 v[202:203], v[18:19], 0, v[252:253]
	v_mad_u64_u32 v[200:201], vcc, v246, s11, v[202:203]
	s_mov_b32 s100, 0xb000
	s_mov_b32 s101, 0
	v_lshl_add_u64 v[194:195], v[192:193], 0, s[100:101]
	v_lshl_add_u64 v[196:197], v[194:195], 0, s[100:101]
	v_lshl_add_u64 v[198:199], v[196:197], 0, s[100:101]
	v_lshl_add_u64 v[202:203], v[200:201], 0, s[100:101]
	v_lshl_add_u64 v[204:205], v[202:203], 0, s[100:101]
	v_lshl_add_u64 v[206:207], v[204:205], 0, s[100:101]
	s_cmp_lt_u32 s98, 4
	s_cbranch_scc0 .Lsgt0_a
	global_load_dwordx4 v[154:157], v[192:193], off offset:640
	global_load_dwordx4 v[158:161], v[194:195], off offset:640
	global_load_dwordx4 v[162:165], v[196:197], off offset:640
	global_load_dwordx4 v[166:169], v[198:199], off offset:640
	global_load_dwordx4 v[170:173], v[200:201], off offset:640
	global_load_dwordx4 v[174:177], v[202:203], off offset:640
	global_load_dwordx4 v[178:181], v[204:205], off offset:640
	global_load_dwordx4 v[208:211], v[206:207], off offset:640
.Lsgt0_a:
	global_load_dwordx4 v[58:61], v[192:193], off
	global_load_dwordx4 v[62:65], v[194:195], off
	global_load_dwordx4 v[66:69], v[196:197], off
	global_load_dwordx4 v[70:73], v[198:199], off
	global_load_dwordx4 v[74:77], v[200:201], off
	global_load_dwordx4 v[78:81], v[202:203], off
	global_load_dwordx4 v[82:85], v[204:205], off
	global_load_dwordx4 v[86:89], v[206:207], off
	global_load_dwordx4 v[90:93], v[192:193], off offset:128
	global_load_dwordx4 v[94:97], v[194:195], off offset:128
	global_load_dwordx4 v[98:101], v[196:197], off offset:128
	global_load_dwordx4 v[102:105], v[198:199], off offset:128
	global_load_dwordx4 v[106:109], v[200:201], off offset:128
	global_load_dwordx4 v[110:113], v[202:203], off offset:128
	global_load_dwordx4 v[114:117], v[204:205], off offset:128
	global_load_dwordx4 v[118:121], v[206:207], off offset:128
	global_load_dwordx4 v[122:125], v[192:193], off offset:256
	global_load_dwordx4 v[126:129], v[194:195], off offset:256
	global_load_dwordx4 v[130:133], v[196:197], off offset:256
	global_load_dwordx4 v[134:137], v[198:199], off offset:256
	global_load_dwordx4 v[138:141], v[200:201], off offset:256
	global_load_dwordx4 v[142:145], v[202:203], off offset:256
	global_load_dwordx4 v[146:149], v[204:205], off offset:256
	global_load_dwordx4 v[150:153], v[206:207], off offset:256
	s_waitcnt vmcnt(16)
	ds_write_b128 v248, v[58:61]
	ds_write_b128 v248, v[62:65] offset:1152
	ds_write_b128 v248, v[66:69] offset:2304
	ds_write_b128 v248, v[70:73] offset:3456
	ds_write_b128 v248, v[74:77] offset:4608
	ds_write_b128 v248, v[78:81] offset:5760
	ds_write_b128 v248, v[82:85] offset:6912
	ds_write_b128 v248, v[86:89] offset:8064
	s_waitcnt lgkmcnt(0)
	ds_read_b128 v[212:215], v249
	ds_read_b128 v[228:231], v249 offset:4608
	ds_read_b128 v[216:219], v249 offset:32
	ds_read_b128 v[234:237], v249 offset:4640
	ds_read_b128 v[220:223], v249 offset:64
	ds_read_b128 v[238:241], v249 offset:4672
	ds_read_b128 v[224:227], v249 offset:96
	ds_read_b128 v[242:245], v249 offset:4704
	s_waitcnt lgkmcnt(6)
	v_mfma_f32_32x32x16_bf16 v[0:15], v[212:215], v[228:231], 0
	s_waitcnt lgkmcnt(4)
	v_mfma_f32_32x32x16_bf16 v[0:15], v[216:219], v[234:237], v[0:15]
	s_waitcnt lgkmcnt(2)
	v_mfma_f32_32x32x16_bf16 v[0:15], v[220:223], v[238:241], v[0:15]
	s_waitcnt lgkmcnt(0)
	v_mfma_f32_32x32x16_bf16 v[0:15], v[224:227], v[242:245], v[0:15]
	global_load_dwordx4 v[58:61], v[192:193], off offset:384
	global_load_dwordx4 v[62:65], v[194:195], off offset:384
	global_load_dwordx4 v[66:69], v[196:197], off offset:384
	global_load_dwordx4 v[70:73], v[198:199], off offset:384
	global_load_dwordx4 v[74:77], v[200:201], off offset:384
	global_load_dwordx4 v[78:81], v[202:203], off offset:384
	global_load_dwordx4 v[82:85], v[204:205], off offset:384
	global_load_dwordx4 v[86:89], v[206:207], off offset:384
	s_waitcnt vmcnt(16)
	ds_write_b128 v248, v[90:93]
	ds_write_b128 v248, v[94:97] offset:1152
	ds_write_b128 v248, v[98:101] offset:2304
	ds_write_b128 v248, v[102:105] offset:3456
	ds_write_b128 v248, v[106:109] offset:4608
	ds_write_b128 v248, v[110:113] offset:5760
	ds_write_b128 v248, v[114:117] offset:6912
	ds_write_b128 v248, v[118:121] offset:8064
	s_waitcnt lgkmcnt(0)
; template <int MODE>
; __device__ __forceinline__ void small_gemm(LAS unsigned char* lds, const bf16* A, const bf16* Bt, int N, int K, bf16* O, int ldc, int act_cols, const float* bias, const bf16* Yv, int ldy, int it0, int it1) {
;     ...
; #pragma unroll 4
;         for (int ks = 0; ks < nks; ++ks) {
;             const bfx8 a = *(const bfx8*)(ap + 16 * ks);
;             const bfx8 b0 = *(const bfx8*)(bp + 16 * ks);
;             acc0 = __builtin_amdgcn_mfma_f32_32x32x16_bf16(b0, a, acc0, 0, 0, 0);
;             if (MODE == 3) { const bfx8 b1 = *(const bfx8*)(bp + (size_t)128 * K + 16 * ks); acc1 = __builtin_amdgcn_mfma_f32_32x32x16_bf16(b1, a, acc1, 0, 0, 0); }
;         }
	ds_read_b128 v[212:215], v249
	ds_read_b128 v[228:231], v249 offset:4608
	ds_read_b128 v[216:219], v249 offset:32
	ds_read_b128 v[234:237], v249 offset:4640
	ds_read_b128 v[220:223], v249 offset:64
	ds_read_b128 v[238:241], v249 offset:4672
	ds_read_b128 v[224:227], v249 offset:96
	ds_read_b128 v[242:245], v249 offset:4704
	s_waitcnt lgkmcnt(6)
	v_mfma_f32_32x32x16_bf16 v[0:15], v[212:215], v[228:231], v[0:15]
	s_waitcnt lgkmcnt(4)
	v_mfma_f32_32x32x16_bf16 v[0:15], v[216:219], v[234:237], v[0:15]
	s_waitcnt lgkmcnt(2)
	v_mfma_f32_32x32x16_bf16 v[0:15], v[220:223], v[238:241], v[0:15]
	s_waitcnt lgkmcnt(0)
	v_mfma_f32_32x32x16_bf16 v[0:15], v[224:227], v[242:245], v[0:15]
	global_load_dwordx4 v[90:93], v[192:193], off offset:512
	global_load_dwordx4 v[94:97], v[194:195], off offset:512
	global_load_dwordx4 v[98:101], v[196:197], off offset:512
	global_load_dwordx4 v[102:105], v[198:199], off offset:512
	global_load_dwordx4 v[106:109], v[200:201], off offset:512
	global_load_dwordx4 v[110:113], v[202:203], off offset:512
	global_load_dwordx4 v[114:117], v[204:205], off offset:512
	global_load_dwordx4 v[118:121], v[206:207], off offset:512
	s_waitcnt vmcnt(16)
	ds_write_b128 v248, v[122:125]
	ds_write_b128 v248, v[126:129] offset:1152
	ds_write_b128 v248, v[130:133] offset:2304
	ds_write_b128 v248, v[134:137] offset:3456
	ds_write_b128 v248, v[138:141] offset:4608
	ds_write_b128 v248, v[142:145] offset:5760
	ds_write_b128 v248, v[146:149] offset:6912
	ds_write_b128 v248, v[150:153] offset:8064
	s_waitcnt lgkmcnt(0)
	ds_read_b128 v[212:215], v249
	ds_read_b128 v[228:231], v249 offset:4608
	ds_read_b128 v[216:219], v249 offset:32
	ds_read_b128 v[234:237], v249 offset:4640
	ds_read_b128 v[220:223], v249 offset:64
	ds_read_b128 v[238:241], v249 offset:4672
	ds_read_b128 v[224:227], v249 offset:96
	ds_read_b128 v[242:245], v249 offset:4704
	s_waitcnt lgkmcnt(6)
	v_mfma_f32_32x32x16_bf16 v[0:15], v[212:215], v[228:231], v[0:15]
	s_waitcnt lgkmcnt(4)
	v_mfma_f32_32x32x16_bf16 v[0:15], v[216:219], v[234:237], v[0:15]
	s_waitcnt lgkmcnt(2)
	v_mfma_f32_32x32x16_bf16 v[0:15], v[220:223], v[238:241], v[0:15]
	s_waitcnt lgkmcnt(0)
	v_mfma_f32_32x32x16_bf16 v[0:15], v[224:227], v[242:245], v[0:15]
	s_waitcnt vmcnt(8)
	ds_write_b128 v248, v[58:61]
	ds_write_b128 v248, v[62:65] offset:1152
	ds_write_b128 v248, v[66:69] offset:2304
	ds_write_b128 v248, v[70:73] offset:3456
	ds_write_b128 v248, v[74:77] offset:4608
	ds_write_b128 v248, v[78:81] offset:5760
	ds_write_b128 v248, v[82:85] offset:6912
	ds_write_b128 v248, v[86:89] offset:8064
	s_waitcnt lgkmcnt(0)
	ds_read_b128 v[212:215], v249
	ds_read_b128 v[228:231], v249 offset:4608
	ds_read_b128 v[216:219], v249 offset:32
	ds_read_b128 v[234:237], v249 offset:4640
	ds_read_b128 v[220:223], v249 offset:64
	ds_read_b128 v[238:241], v249 offset:4672
	ds_read_b128 v[224:227], v249 offset:96
	ds_read_b128 v[242:245], v249 offset:4704
	s_waitcnt lgkmcnt(6)
	v_mfma_f32_32x32x16_bf16 v[0:15], v[212:215], v[228:231], v[0:15]
	s_waitcnt lgkmcnt(4)
	v_mfma_f32_32x32x16_bf16 v[0:15], v[216:219], v[234:237], v[0:15]
	s_waitcnt lgkmcnt(2)
	v_mfma_f32_32x32x16_bf16 v[0:15], v[220:223], v[238:241], v[0:15]
	s_waitcnt lgkmcnt(0)
	v_mfma_f32_32x32x16_bf16 v[0:15], v[224:227], v[242:245], v[0:15]
	s_waitcnt vmcnt(0)
	ds_write_b128 v248, v[90:93]
	ds_write_b128 v248, v[94:97] offset:1152
	ds_write_b128 v248, v[98:101] offset:2304
	ds_write_b128 v248, v[102:105] offset:3456
	ds_write_b128 v248, v[106:109] offset:4608
	ds_write_b128 v248, v[110:113] offset:5760
	ds_write_b128 v248, v[114:117] offset:6912
	ds_write_b128 v248, v[118:121] offset:8064
	s_waitcnt lgkmcnt(0)
	ds_read_b128 v[212:215], v249
	ds_read_b128 v[228:231], v249 offset:4608
	ds_read_b128 v[216:219], v249 offset:32
	ds_read_b128 v[234:237], v249 offset:4640
	ds_read_b128 v[220:223], v249 offset:64
	ds_read_b128 v[238:241], v249 offset:4672
	ds_read_b128 v[224:227], v249 offset:96
	ds_read_b128 v[242:245], v249 offset:4704
	s_waitcnt lgkmcnt(6)
	v_mfma_f32_32x32x16_bf16 v[0:15], v[212:215], v[228:231], v[0:15]
	s_waitcnt lgkmcnt(4)
	v_mfma_f32_32x32x16_bf16 v[0:15], v[216:219], v[234:237], v[0:15]
	s_waitcnt lgkmcnt(2)
	v_mfma_f32_32x32x16_bf16 v[0:15], v[220:223], v[238:241], v[0:15]
	s_waitcnt lgkmcnt(0)
	v_mfma_f32_32x32x16_bf16 v[0:15], v[224:227], v[242:245], v[0:15]
	s_cmp_lt_u32 s98, 4
	s_cbranch_scc0 .Lsgt0_b
	ds_write_b128 v248, v[154:157]
	ds_write_b128 v248, v[158:161] offset:1152
	ds_write_b128 v248, v[162:165] offset:2304
	ds_write_b128 v248, v[166:169] offset:3456
	ds_write_b128 v248, v[170:173] offset:4608
	ds_write_b128 v248, v[174:177] offset:5760
	ds_write_b128 v248, v[178:181] offset:6912
	ds_write_b128 v248, v[208:211] offset:8064
	s_waitcnt lgkmcnt(0)
	ds_read_b128 v[212:215], v249
	ds_read_b128 v[228:231], v249 offset:4608
	ds_read_b128 v[216:219], v249 offset:32
	ds_read_b128 v[234:237], v249 offset:4640
	ds_read_b128 v[220:223], v249 offset:64
	ds_read_b128 v[238:241], v249 offset:4672
	ds_read_b128 v[224:227], v249 offset:96
	ds_read_b128 v[242:245], v249 offset:4704
	s_waitcnt lgkmcnt(6)
	v_mfma_f32_32x32x16_bf16 v[0:15], v[212:215], v[228:231], v[0:15]
	s_waitcnt lgkmcnt(4)
	v_mfma_f32_32x32x16_bf16 v[0:15], v[216:219], v[234:237], v[0:15]
	s_waitcnt lgkmcnt(2)
	v_mfma_f32_32x32x16_bf16 v[0:15], v[220:223], v[238:241], v[0:15]
	s_waitcnt lgkmcnt(0)
	v_mfma_f32_32x32x16_bf16 v[0:15], v[224:227], v[242:245], v[0:15]
; __device__ __forceinline__ unsigned cvt_pk_bf16(float lo, float hi) { unsigned r; asm volatile("v_cvt_pk_bf16_f32 %0, %1, %2" : "=v"(r) : "v"(lo), "v"(hi)); return r; }
; __device__ __forceinline__ float bf_lo(unsigned w) { return __uint_as_float(w << 16); }
; __device__ __forceinline__ float bf_hi(unsigned w) { return __uint_as_float(w & 0xffff0000u); }
; __device__ __forceinline__ float sigmoid_f(float x) { return __builtin_amdgcn_rcpf(1.0f + __expf(-x)); }
; __device__ __forceinline__ float silu_f(float x) { return x * sigmoid_f(x); }
; __device__ __forceinline__ float gelu_t(float x) { const float u = 1.5957691216057308f * (x + 0.044715f * x * x * x); return x * sigmoid_f(u); }
; template <int MODE>
; __device__ __forceinline__ void small_gemm(LAS unsigned char* lds, const bf16* A, const bf16* Bt, int N, int K, bf16* O, int ldc, int act_cols, const float* bias, const bf16* Yv, int ldy, int it0, int it1) {
;     ...
;         __syncthreads();
; #pragma unroll
;         for (int r = 0; r < 16; ++r) { red[(wave * 16 + r) * 64 + lane] = acc0[r]; if (MODE == 3) red[8192 + (wave * 16 + r) * 64 + lane] = acc1[r]; }
;         __syncthreads();
;         float v0[2], v1[2];
; #pragma unroll
;         for (int e = 0; e < 2; ++e) { float s0 = 0.f, s1 = 0.f;
; #pragma unroll
;             for (int w = 0; w < 8; ++w) { s0 += red[(w * 16 + 2 * wave + e) * 64 + lane]; if (MODE == 3) s1 += red[8192 + (w * 16 + 2 * wave + e) * 64 + lane]; }
;             v0[e] = s0; v1[e] = s1; }
;         const int reg = 2 * wave;
;         const int col = 32 * ct + (reg & 3) + 8 * (reg >> 2) + 4 * hh;
;         const size_t row = (size_t)(32 * rt + tl);
;         float o0 = v0[0], o1 = v0[1];
;         if (MODE == 1) { if (col < act_cols) { o0 = gelu_t(o0); o1 = gelu_t(o1); } }
;         if (MODE == 2) { const unsigned y = *(const unsigned*)(Yv + row * ldy + col); o0 = bf_lo(y) * pg8::sigmoid_f(o0 + bias[col]); o1 = bf_hi(y) * pg8::sigmoid_f(o1 + bias[col + 1]); }
;         if (MODE == 3) { o0 = pg8::silu_f(o0) * v1[0]; o1 = pg8::silu_f(o1) * v1[1]; }
;         *(unsigned*)(O + row * ldc + col) = cvt_pk_bf16(o0, o1);
.Lsgt0_b:
	s_barrier
	v_add_u32_e32 v26, s3, v23
	v_ashrrev_i32_e32 v27, 31, v26
	v_lshl_add_u64 v[28:29], s[6:7], 0, v[16:17]
	v_lshl_add_u64 v[26:27], v[26:27], 1, v[28:29]
	s_nop 11
	ds_write2st64_b32 v24, v0, v1 offset1:1
	ds_write2st64_b32 v24, v2, v3 offset0:2 offset1:3
	ds_write2st64_b32 v24, v4, v5 offset0:4 offset1:5
	ds_write2st64_b32 v24, v6, v7 offset0:6 offset1:7
	ds_write2st64_b32 v24, v8, v9 offset0:8 offset1:9
	ds_write2st64_b32 v24, v10, v11 offset0:10 offset1:11
	ds_write2st64_b32 v24, v12, v13 offset0:12 offset1:13
	ds_write2st64_b32 v24, v14, v15 offset0:14 offset1:15
	s_waitcnt lgkmcnt(0)
	s_barrier
	ds_read2st64_b32 v[0:1], v25 offset1:1
	ds_read2st64_b32 v[2:3], v25 offset0:16 offset1:17
	ds_read2st64_b32 v[4:5], v25 offset0:32 offset1:33
	ds_read2st64_b32 v[6:7], v25 offset0:48 offset1:49
	ds_read2st64_b32 v[8:9], v25 offset0:64 offset1:65
	ds_read2st64_b32 v[10:11], v25 offset0:80 offset1:81
	ds_read2st64_b32 v[12:13], v25 offset0:96 offset1:97
	ds_read2st64_b32 v[14:15], v25 offset0:112 offset1:113
	s_waitcnt lgkmcnt(7)
	v_add_f32_e32 v0, 0, v0
	v_add_f32_e32 v1, 0, v1
	s_waitcnt lgkmcnt(6)
	v_add_f32_e32 v0, v0, v2
	v_add_f32_e32 v1, v1, v3
	s_waitcnt lgkmcnt(5)
	v_add_f32_e32 v0, v0, v4
	v_add_f32_e32 v1, v1, v5
	s_waitcnt lgkmcnt(4)
	v_add_f32_e32 v0, v0, v6
	v_add_f32_e32 v1, v1, v7
	s_waitcnt lgkmcnt(3)
	v_add_f32_e32 v0, v0, v8
	v_add_f32_e32 v1, v1, v9
	s_waitcnt lgkmcnt(2)
	v_add_f32_e32 v0, v0, v10
	v_add_f32_e32 v1, v1, v11
	s_waitcnt lgkmcnt(1)
	v_add_f32_e32 v0, v0, v12
	v_add_f32_e32 v1, v1, v13
	s_waitcnt lgkmcnt(0)
	v_add_f32_e32 v0, v0, v14
	v_add_f32_e32 v1, v1, v15
	v_cvt_pk_bf16_f32 v0, v0, v1
	global_store_dword v[26:27], v0, off
	s_branch .LBB0_279

; template <int MODE>
; __device__ __forceinline__ void small_gemm(LAS unsigned char* lds, const bf16* A, const bf16* Bt, int N, int K, bf16* O, int ldc, int act_cols, const float* bias, const bf16* Yv, int ldy, int it0, int it1) {
;     ...
;     for (int it = it0; it < it1; ++it) {
;         const int item = BX + it * GSZ; if (item >= nitems) break;
;         const int rt = item & 3, ct = item >> 2;
;         const int hc = 32 * ct + tl;
;         const int brow = (MODE == 3) ? (256 * (hc >> 7) + (hc & 127)) : hc;
;         const bf16* ap = A + (size_t)(32 * rt + tl) * K + wave * kw + 8 * hh;
;         const bf16* bp = Bt + (size_t)brow * K + wave * kw + 8 * hh;
;         v16f acc0, acc1;
; #pragma unroll
;         for (int r = 0; r < 16; ++r) { acc0[r] = 0.f; acc1[r] = 0.f; }
; #pragma unroll 4
;         for (int ks = 0; ks < nks; ++ks) {
;             const bfx8 a = *(const bfx8*)(ap + 16 * ks);
;             const bfx8 b0 = *(const bfx8*)(bp + 16 * ks);
;             acc0 = __builtin_amdgcn_mfma_f32_32x32x16_bf16(b0, a, acc0, 0, 0, 0);
;             if (MODE == 3) { const bfx8 b1 = *(const bfx8*)(bp + (size_t)128 * K + 16 * ks); acc1 = __builtin_amdgcn_mfma_f32_32x32x16_bf16(b1, a, acc1, 0, 0, 0); }
;         }
.LBB0_312:
	s_add_i32 s11, s11, s94
	s_cmpk_gt_i32 s11, 0x7f
	s_mov_b64 s[8:9], -1
	s_cbranch_scc1 .LBB0_311
	s_and_b32 s3, s13, 0xffffffe0
	v_or_b32_e32 v0, s3, v22
	v_mad_i64_i32 v[54:55], s[0:1], v0, s10, v[20:21]
	v_and_b32_e32 v246, 63, v182
	v_lshrrev_b32_e32 v247, 6, v182
	s_nop 0
	v_readfirstlane_b32 s98, v247
	s_and_b32 s8, s14, 0x60
	s_mov_b32 s100, s8
	v_or_b32_e32 v16, s8, v22
	v_mad_u64_u32 v[56:57], s[0:1], v16, s10, v[18:19]
	s_add_i32 s12, s12, 1
	s_add_i32 s13, s13, s46
	s_add_i32 s14, s14, s71
	v_lshlrev_b32_e32 v16, 11, v16
	s_cmp_gt_u32 s12, 2
	s_cselect_b64 s[8:9], -1, 0
	s_min_u32 s99, s98, 4
	s_lshl_b32 s99, s99, 7
	s_mul_i32 m0, s98, 0x280
	s_add_i32 s99, s99, m0
	s_mul_i32 m0, s98, 0x2c0
	s_sub_i32 s99, s99, m0
	v_lshrrev_b32_e32 v247, 3, v246
	v_and_b32_e32 v250, 7, v246
	v_lshlrev_b32_e32 v250, 4, v250
	s_mul_i32 m0, s98, 0x2400
	s_add_i32 m0, m0, 0x10000
	v_mul_u32_u24_e32 v248, 0x90, v247
	v_add3_u32 v248, v248, v250, m0
	v_mul_u32_u24_e32 v249, 0x90, v22
	v_lshrrev_b32_e32 v252, 5, v246
	v_lshl_add_u32 v249, v252, 4, v249
	v_add_u32_e32 v249, m0, v249
	v_lshlrev_b32_e32 v252, 4, v252
	v_sub_u32_e32 v252, v250, v252
	v_add_u32_e32 v252, s99, v252
	v_ashrrev_i32_e32 v253, 31, v252
	v_add_u32_e32 v246, s3, v247
	v_lshl_add_u64 v[194:195], v[20:21], 0, v[252:253]
	v_mad_u64_u32 v[192:193], vcc, v246, s10, v[194:195]
	v_add_u32_e32 v246, s100, v247
	v_lshl_add_u64 v[202:203], v[18:19], 0, v[252:253]
	v_mad_u64_u32 v[200:201], vcc, v246, s10, v[202:203]
	s_mov_b32 s100, 0xb000
	s_mov_b32 s101, 0
	v_lshl_add_u64 v[194:195], v[192:193], 0, s[100:101]
	v_lshl_add_u64 v[196:197], v[194:195], 0, s[100:101]
	v_lshl_add_u64 v[198:199], v[196:197], 0, s[100:101]
	v_lshl_add_u64 v[202:203], v[200:201], 0, s[100:101]
	v_lshl_add_u64 v[204:205], v[202:203], 0, s[100:101]
	v_lshl_add_u64 v[206:207], v[204:205], 0, s[100:101]
	s_cmp_lt_u32 s98, 4
	s_cbranch_scc0 .Lsgt1_a
	global_load_dwordx4 v[154:157], v[192:193], off offset:640
	global_load_dwordx4 v[158:161], v[194:195], off offset:640
	global_load_dwordx4 v[162:165], v[196:197], off offset:640
	global_load_dwordx4 v[166:169], v[198:199], off offset:640
	global_load_dwordx4 v[170:173], v[200:201], off offset:640
	global_load_dwordx4 v[174:177], v[202:203], off offset:640
	global_load_dwordx4 v[178:181], v[204:205], off offset:640
	global_load_dwordx4 v[208:211], v[206:207], off offset:640

; template <int MODE>
; __device__ __forceinline__ void small_gemm(LAS unsigned char* lds, const bf16* A, const bf16* Bt, int N, int K, bf16* O, int ldc, int act_cols, const float* bias, const bf16* Yv, int ldy, int it0, int it1) {
;     ...
;     for (int it = it0; it < it1; ++it) {
;         const int item = BX + it * GSZ; if (item >= nitems) break;
;         const int rt = item & 3, ct = item >> 2;
;         const int hc = 32 * ct + tl;
;         const int brow = (MODE == 3) ? (256 * (hc >> 7) + (hc & 127)) : hc;
;         const bf16* ap = A + (size_t)(32 * rt + tl) * K + wave * kw + 8 * hh;
;         const bf16* bp = Bt + (size_t)brow * K + wave * kw + 8 * hh;
;         v16f acc0, acc1;
; #pragma unroll
;         for (int r = 0; r < 16; ++r) { acc0[r] = 0.f; acc1[r] = 0.f; }
; #pragma unroll 4
;         for (int ks = 0; ks < nks; ++ks) {
;             const bfx8 a = *(const bfx8*)(ap + 16 * ks);
;             const bfx8 b0 = *(const bfx8*)(bp + 16 * ks);
;             acc0 = __builtin_amdgcn_mfma_f32_32x32x16_bf16(b0, a, acc0, 0, 0, 0);
;             if (MODE == 3) { const bfx8 b1 = *(const bfx8*)(bp + (size_t)128 * K + 16 * ks); acc1 = __builtin_amdgcn_mfma_f32_32x32x16_bf16(b1, a, acc1, 0, 0, 0); }
;         }
.LBB0_1186:
	s_add_i32 s12, s12, s94
	s_cmpk_gt_i32 s12, 0x7f
	s_mov_b64 s[10:11], -1
	s_cbranch_scc1 .LBB0_1185
	s_and_b32 s3, s14, 0xffffffe0
	v_or_b32_e32 v0, s3, v22
	v_mad_i64_i32 v[54:55], s[0:1], v0, s13, v[20:21]
	v_and_b32_e32 v246, 63, v182
	v_lshrrev_b32_e32 v247, 6, v182
	s_nop 0
	v_readfirstlane_b32 s98, v247
	s_and_b32 s10, s15, 0x60
	s_mov_b32 s100, s10
	v_or_b32_e32 v16, s10, v22
	v_mad_u64_u32 v[56:57], s[0:1], v16, s13, v[18:19]
	s_add_i32 s44, s44, -1
	s_add_i32 s14, s14, s46
	s_add_i32 s15, s15, s71
	v_lshlrev_b32_e32 v16, 11, v16
	s_cmp_eq_u32 s44, 0
	s_cselect_b64 s[10:11], -1, 0
	s_min_u32 s99, s98, 4
	s_lshl_b32 s99, s99, 7
	s_mul_i32 m0, s98, 0x280
	s_add_i32 s99, s99, m0
	s_mul_i32 m0, s98, 0x2c0
	s_sub_i32 s99, s99, m0
	v_lshrrev_b32_e32 v247, 3, v246
	v_and_b32_e32 v250, 7, v246
	v_lshlrev_b32_e32 v250, 4, v250
	s_mul_i32 m0, s98, 0x2400
	s_add_i32 m0, m0, 0x10000
	v_mul_u32_u24_e32 v248, 0x90, v247
	v_add3_u32 v248, v248, v250, m0
	v_mul_u32_u24_e32 v249, 0x90, v22
	v_lshrrev_b32_e32 v252, 5, v246
	v_lshl_add_u32 v249, v252, 4, v249
	v_add_u32_e32 v249, m0, v249
	v_lshlrev_b32_e32 v252, 4, v252
	v_sub_u32_e32 v252, v250, v252
	v_add_u32_e32 v252, s99, v252
	v_ashrrev_i32_e32 v253, 31, v252
	v_add_u32_e32 v246, s3, v247
	v_lshl_add_u64 v[194:195], v[20:21], 0, v[252:253]
	v_mad_u64_u32 v[192:193], vcc, v246, s13, v[194:195]
	v_add_u32_e32 v246, s100, v247
	v_lshl_add_u64 v[202:203], v[18:19], 0, v[252:253]
	v_mad_u64_u32 v[200:201], vcc, v246, s13, v[202:203]
	s_mov_b32 s100, 0xb000
	s_mov_b32 s101, 0
	v_lshl_add_u64 v[194:195], v[192:193], 0, s[100:101]
	v_lshl_add_u64 v[196:197], v[194:195], 0, s[100:101]
	v_lshl_add_u64 v[198:199], v[196:197], 0, s[100:101]
	v_lshl_add_u64 v[202:203], v[200:201], 0, s[100:101]
	v_lshl_add_u64 v[204:205], v[202:203], 0, s[100:101]
	v_lshl_add_u64 v[206:207], v[204:205], 0, s[100:101]
	s_cmp_lt_u32 s98, 4
	s_cbranch_scc0 .Lsgt2_a
	global_load_dwordx4 v[154:157], v[192:193], off offset:640
	global_load_dwordx4 v[158:161], v[194:195], off offset:640
	global_load_dwordx4 v[162:165], v[196:197], off offset:640
	global_load_dwordx4 v[166:169], v[198:199], off offset:640
	global_load_dwordx4 v[170:173], v[200:201], off offset:640
	global_load_dwordx4 v[174:177], v[202:203], off offset:640
	global_load_dwordx4 v[178:181], v[204:205], off offset:640
	global_load_dwordx4 v[208:211], v[206:207], off offset:640

; __device__ __forceinline__ unsigned cvt_pk_bf16(float lo, float hi) { unsigned r; asm volatile("v_cvt_pk_bf16_f32 %0, %1, %2" : "=v"(r) : "v"(lo), "v"(hi)); return r; }
; __device__ __forceinline__ float bf_lo(unsigned w) { return __uint_as_float(w << 16); }
; __device__ __forceinline__ float bf_hi(unsigned w) { return __uint_as_float(w & 0xffff0000u); }
; __device__ __forceinline__ float sigmoid_f(float x) { return __builtin_amdgcn_rcpf(1.0f + __expf(-x)); }
; __device__ __forceinline__ float silu_f(float x) { return x * sigmoid_f(x); }
; __device__ __forceinline__ float gelu_t(float x) { const float u = 1.5957691216057308f * (x + 0.044715f * x * x * x); return x * sigmoid_f(u); }
; template <int MODE>
; __device__ __forceinline__ void small_gemm(LAS unsigned char* lds, const bf16* A, const bf16* Bt, int N, int K, bf16* O, int ldc, int act_cols, const float* bias, const bf16* Yv, int ldy, int it0, int it1) {
;     ...
;         __syncthreads();
; #pragma unroll
;         for (int r = 0; r < 16; ++r) { red[(wave * 16 + r) * 64 + lane] = acc0[r]; if (MODE == 3) red[8192 + (wave * 16 + r) * 64 + lane] = acc1[r]; }
;         __syncthreads();
;         float v0[2], v1[2];
; #pragma unroll
;         for (int e = 0; e < 2; ++e) { float s0 = 0.f, s1 = 0.f;
; #pragma unroll
;             for (int w = 0; w < 8; ++w) { s0 += red[(w * 16 + 2 * wave + e) * 64 + lane]; if (MODE == 3) s1 += red[8192 + (w * 16 + 2 * wave + e) * 64 + lane]; }
;             v0[e] = s0; v1[e] = s1; }
;         const int reg = 2 * wave;
;         const int col = 32 * ct + (reg & 3) + 8 * (reg >> 2) + 4 * hh;
;         const size_t row = (size_t)(32 * rt + tl);
;         float o0 = v0[0], o1 = v0[1];
;         if (MODE == 1) { if (col < act_cols) { o0 = gelu_t(o0); o1 = gelu_t(o1); } }
;         if (MODE == 2) { const unsigned y = *(const unsigned*)(Yv + row * ldy + col); o0 = bf_lo(y) * pg8::sigmoid_f(o0 + bias[col]); o1 = bf_hi(y) * pg8::sigmoid_f(o1 + bias[col + 1]); }
;         if (MODE == 3) { o0 = pg8::silu_f(o0) * v1[0]; o1 = pg8::silu_f(o1) * v1[1]; }
;         *(unsigned*)(O + row * ldc + col) = cvt_pk_bf16(o0, o1);
.Lsgt2_b:
	s_barrier
	v_add_u32_e32 v26, s3, v23
	v_ashrrev_i32_e32 v27, 31, v26
	v_lshl_add_u64 v[28:29], s[4:5], 0, v[16:17]
	v_lshl_add_u64 v[26:27], v[26:27], 1, v[28:29]
	s_nop 11
	ds_write2st64_b32 v24, v0, v1 offset1:1
	ds_write2st64_b32 v24, v2, v3 offset0:2 offset1:3
	ds_write2st64_b32 v24, v4, v5 offset0:4 offset1:5
	ds_write2st64_b32 v24, v6, v7 offset0:6 offset1:7
	ds_write2st64_b32 v24, v8, v9 offset0:8 offset1:9
	ds_write2st64_b32 v24, v10, v11 offset0:10 offset1:11
	ds_write2st64_b32 v24, v12, v13 offset0:12 offset1:13
	ds_write2st64_b32 v24, v14, v15 offset0:14 offset1:15
	s_waitcnt lgkmcnt(0)
	s_barrier
	ds_read2st64_b32 v[0:1], v25 offset1:1
	ds_read2st64_b32 v[2:3], v25 offset0:16 offset1:17
	ds_read2st64_b32 v[4:5], v25 offset0:32 offset1:33
	ds_read2st64_b32 v[6:7], v25 offset0:48 offset1:49
	ds_read2st64_b32 v[8:9], v25 offset0:64 offset1:65
	ds_read2st64_b32 v[10:11], v25 offset0:80 offset1:81
	ds_read2st64_b32 v[12:13], v25 offset0:96 offset1:97
	ds_read2st64_b32 v[14:15], v25 offset0:112 offset1:113
	s_waitcnt lgkmcnt(7)
	v_add_f32_e32 v0, 0, v0
	v_add_f32_e32 v1, 0, v1
	s_waitcnt lgkmcnt(6)
	v_add_f32_e32 v0, v0, v2
	v_add_f32_e32 v1, v1, v3
	s_waitcnt lgkmcnt(5)
	v_add_f32_e32 v0, v0, v4
	v_add_f32_e32 v1, v1, v5
	s_waitcnt lgkmcnt(4)
	v_add_f32_e32 v0, v0, v6
	v_add_f32_e32 v1, v1, v7
	s_waitcnt lgkmcnt(3)
	v_add_f32_e32 v0, v0, v8
	v_add_f32_e32 v1, v1, v9
	s_waitcnt lgkmcnt(2)
	v_add_f32_e32 v0, v0, v10
	v_add_f32_e32 v1, v1, v11
	s_waitcnt lgkmcnt(1)
	v_add_f32_e32 v0, v0, v12
	v_add_f32_e32 v1, v1, v13
	s_waitcnt lgkmcnt(0)
	v_add_f32_e32 v0, v0, v14
	v_add_f32_e32 v1, v1, v15
	v_cvt_pk_bf16_f32 v0, v0, v1
	global_store_dword v[26:27], v0, off
	s_branch .LBB0_1185

; template <int MODE>
; __device__ __forceinline__ void small_gemm(LAS unsigned char* lds, const bf16* A, const bf16* Bt, int N, int K, bf16* O, int ldc, int act_cols, const float* bias, const bf16* Yv, int ldy, int it0, int it1) {
;     ...
;     for (int it = it0; it < it1; ++it) {
;         const int item = BX + it * GSZ; if (item >= nitems) break;
;         const int rt = item & 3, ct = item >> 2;
;         const int hc = 32 * ct + tl;
;         const int brow = (MODE == 3) ? (256 * (hc >> 7) + (hc & 127)) : hc;
;         const bf16* ap = A + (size_t)(32 * rt + tl) * K + wave * kw + 8 * hh;
;         const bf16* bp = Bt + (size_t)brow * K + wave * kw + 8 * hh;
;         v16f acc0, acc1;
; #pragma unroll
;         for (int r = 0; r < 16; ++r) { acc0[r] = 0.f; acc1[r] = 0.f; }
; #pragma unroll 4
;         for (int ks = 0; ks < nks; ++ks) {
;             const bfx8 a = *(const bfx8*)(ap + 16 * ks);
;             const bfx8 b0 = *(const bfx8*)(bp + 16 * ks);
;             acc0 = __builtin_amdgcn_mfma_f32_32x32x16_bf16(b0, a, acc0, 0, 0, 0);
;             if (MODE == 3) { const bfx8 b1 = *(const bfx8*)(bp + (size_t)128 * K + 16 * ks); acc1 = __builtin_amdgcn_mfma_f32_32x32x16_bf16(b1, a, acc1, 0, 0, 0); }
;         }
.LBB0_1218:
	s_add_i32 s85, s85, s94
	s_cmpk_gt_i32 s85, 0x7f
	s_mov_b64 s[8:9], -1
	s_cbranch_scc1 .LBB0_1217
	s_and_b32 s3, s2, 0xffffffe0
	v_or_b32_e32 v0, s3, v22
	v_mad_i64_i32 v[54:55], s[0:1], v0, s10, v[20:21]
	v_and_b32_e32 v246, 63, v182
	v_lshrrev_b32_e32 v247, 6, v182
	s_nop 0
	v_readfirstlane_b32 s98, v247
	s_and_b32 s8, s82, 0x60
	s_mov_b32 s100, s8
	v_or_b32_e32 v16, s8, v22
	v_mad_u64_u32 v[56:57], s[0:1], v16, s10, v[18:19]
	s_add_i32 s84, s84, 1
	s_add_i32 s2, s2, s46
	s_add_i32 s82, s82, s71
	v_lshlrev_b32_e32 v16, 11, v16
	s_cmp_gt_u32 s84, 2
	s_cselect_b64 s[8:9], -1, 0
	s_min_u32 s99, s98, 4
	s_lshl_b32 s99, s99, 7
	s_mul_i32 m0, s98, 0x280
	s_add_i32 s99, s99, m0
	s_mul_i32 m0, s98, 0x2c0
	s_sub_i32 s99, s99, m0
	v_lshrrev_b32_e32 v247, 3, v246
	v_and_b32_e32 v250, 7, v246
	v_lshlrev_b32_e32 v250, 4, v250
	s_mul_i32 m0, s98, 0x2400
	s_add_i32 m0, m0, 0x10000
	v_mul_u32_u24_e32 v248, 0x90, v247
	v_add3_u32 v248, v248, v250, m0
	v_mul_u32_u24_e32 v249, 0x90, v22
	v_lshrrev_b32_e32 v252, 5, v246
	v_lshl_add_u32 v249, v252, 4, v249
	v_add_u32_e32 v249, m0, v249
	v_lshlrev_b32_e32 v252, 4, v252
	v_sub_u32_e32 v252, v250, v252
	v_add_u32_e32 v252, s99, v252
	v_ashrrev_i32_e32 v253, 31, v252
	v_add_u32_e32 v246, s3, v247
	v_lshl_add_u64 v[194:195], v[20:21], 0, v[252:253]
	v_mad_u64_u32 v[192:193], vcc, v246, s10, v[194:195]
	v_add_u32_e32 v246, s100, v247
	v_lshl_add_u64 v[202:203], v[18:19], 0, v[252:253]
	v_mad_u64_u32 v[200:201], vcc, v246, s10, v[202:203]
	s_mov_b32 s100, 0xb000
	s_mov_b32 s101, 0
	v_lshl_add_u64 v[194:195], v[192:193], 0, s[100:101]
	v_lshl_add_u64 v[196:197], v[194:195], 0, s[100:101]
	v_lshl_add_u64 v[198:199], v[196:197], 0, s[100:101]
	v_lshl_add_u64 v[202:203], v[200:201], 0, s[100:101]
	v_lshl_add_u64 v[204:205], v[202:203], 0, s[100:101]
	v_lshl_add_u64 v[206:207], v[204:205], 0, s[100:101]
	s_cmp_lt_u32 s98, 4
	s_cbranch_scc0 .Lsgt3_a
	global_load_dwordx4 v[154:157], v[192:193], off offset:640
	global_load_dwordx4 v[158:161], v[194:195], off offset:640
	global_load_dwordx4 v[162:165], v[196:197], off offset:640
	global_load_dwordx4 v[166:169], v[198:199], off offset:640
	global_load_dwordx4 v[170:173], v[200:201], off offset:640
	global_load_dwordx4 v[174:177], v[202:203], off offset:640
	global_load_dwordx4 v[178:181], v[204:205], off offset:640
	global_load_dwordx4 v[208:211], v[206:207], off offset:640
